# GEMM1 epilogue GELU hand-rewritten: abs via VOP3 modifiers, select replaced by fma(-|v|,q*e,max(v,0)), two pairs interleaved so no pk-dependency nops
# speedup vs baseline: 1.0190x; 1.0038x over previous
.LBB0_226:
	s_and_b64 vcc, exec, s[0:1]
	s_cbranch_vccz .LBB0_228
	v_mov_b64_e32 v[232:233], s[50:51]
	v_fma_f32 v234, |v142|, s36, 1.0
	v_fma_f32 v240, |v144|, s36, 1.0
	v_fma_f32 v235, |v143|, s36, 1.0
	v_fma_f32 v241, |v145|, s36, 1.0
	v_pk_mul_f32 v[238:239], v[142:143], v[142:143]
	v_pk_mul_f32 v[244:245], v[144:145], v[144:145]
	v_rcp_f32_e32 v234, v234
	v_rcp_f32_e32 v240, v240
	v_rcp_f32_e32 v235, v235
	v_rcp_f32_e32 v241, v241
	v_pk_mul_f32 v[238:239], v[238:239], s[58:59] op_sel_hi:[1,0]
	v_pk_mul_f32 v[244:245], v[244:245], s[58:59] op_sel_hi:[1,0]
	v_pk_fma_f32 v[236:237], v[234:235], s[38:39], v[232:233] op_sel_hi:[1,0,0]
	v_pk_fma_f32 v[242:243], v[240:241], s[38:39], v[232:233] op_sel_hi:[1,0,0]
	v_exp_f32_e32 v238, v238
	v_exp_f32_e32 v244, v244
	v_pk_fma_f32 v[236:237], v[234:235], v[236:237], s[52:53] op_sel_hi:[1,1,0]
	v_pk_fma_f32 v[242:243], v[240:241], v[242:243], s[52:53] op_sel_hi:[1,1,0]
	v_exp_f32_e32 v239, v239
	v_exp_f32_e32 v245, v245
	v_pk_fma_f32 v[236:237], v[234:235], v[236:237], s[54:55] op_sel_hi:[1,1,0]
	v_pk_fma_f32 v[242:243], v[240:241], v[242:243], s[54:55] op_sel_hi:[1,1,0]
	v_pk_fma_f32 v[236:237], v[234:235], v[236:237], s[56:57] op_sel_hi:[1,1,0]
	v_pk_fma_f32 v[242:243], v[240:241], v[242:243], s[56:57] op_sel_hi:[1,1,0]
	v_pk_mul_f32 v[236:237], v[234:235], v[236:237]
	v_pk_mul_f32 v[242:243], v[240:241], v[242:243]
	v_pk_mul_f32 v[236:237], v[236:237], v[238:239]
	v_pk_mul_f32 v[242:243], v[242:243], v[244:245]
	v_max_f32_e32 v234, 0, v142
	v_max_f32_e32 v240, 0, v144
	v_max_f32_e32 v235, 0, v143
	v_max_f32_e32 v241, 0, v145
	v_fma_f32 v166, -|v142|, v236, v234
	v_fma_f32 v168, -|v144|, v242, v240
	v_fma_f32 v167, -|v143|, v237, v235
	v_fma_f32 v169, -|v145|, v243, v241
	v_fma_f32 v246, |v138|, s36, 1.0
	v_fma_f32 v254, |v140|, s36, 1.0
	v_fma_f32 v247, |v139|, s36, 1.0
	v_fma_f32 v255, |v141|, s36, 1.0
	v_pk_mul_f32 v[244:245], v[138:139], v[138:139]
	v_pk_mul_f32 v[238:239], v[140:141], v[140:141]
	v_rcp_f32_e32 v246, v246
	v_rcp_f32_e32 v254, v254
	v_rcp_f32_e32 v247, v247
	v_rcp_f32_e32 v255, v255
	v_pk_mul_f32 v[244:245], v[244:245], s[58:59] op_sel_hi:[1,0]
	v_pk_mul_f32 v[238:239], v[238:239], s[58:59] op_sel_hi:[1,0]
	v_pk_fma_f32 v[242:243], v[246:247], s[38:39], v[232:233] op_sel_hi:[1,0,0]
	v_pk_fma_f32 v[236:237], v[254:255], s[38:39], v[232:233] op_sel_hi:[1,0,0]
	v_exp_f32_e32 v244, v244
	v_exp_f32_e32 v238, v238
	v_pk_fma_f32 v[242:243], v[246:247], v[242:243], s[52:53] op_sel_hi:[1,1,0]
	v_pk_fma_f32 v[236:237], v[254:255], v[236:237], s[52:53] op_sel_hi:[1,1,0]
	v_exp_f32_e32 v245, v245
	v_exp_f32_e32 v239, v239
	v_pk_fma_f32 v[242:243], v[246:247], v[242:243], s[54:55] op_sel_hi:[1,1,0]
	v_pk_fma_f32 v[236:237], v[254:255], v[236:237], s[54:55] op_sel_hi:[1,1,0]
	v_pk_fma_f32 v[242:243], v[246:247], v[242:243], s[56:57] op_sel_hi:[1,1,0]
	v_pk_fma_f32 v[236:237], v[254:255], v[236:237], s[56:57] op_sel_hi:[1,1,0]
	v_pk_mul_f32 v[242:243], v[246:247], v[242:243]
	v_pk_mul_f32 v[236:237], v[254:255], v[236:237]
	v_pk_mul_f32 v[242:243], v[242:243], v[244:245]
	v_pk_mul_f32 v[236:237], v[236:237], v[238:239]
	v_max_f32_e32 v246, 0, v138
	v_max_f32_e32 v254, 0, v140
	v_max_f32_e32 v247, 0, v139
	v_max_f32_e32 v255, 0, v141
	v_fma_f32 v170, -|v138|, v242, v246
	v_fma_f32 v172, -|v140|, v236, v254
	v_fma_f32 v171, -|v139|, v243, v247
	v_fma_f32 v173, -|v141|, v237, v255

.LBB0_254:
	v_mov_b64_e32 v[232:233], s[50:51]
	v_fma_f32 v234, |v166|, s36, 1.0
	v_fma_f32 v240, |v136|, s36, 1.0
	v_fma_f32 v235, |v167|, s36, 1.0
	v_fma_f32 v241, |v137|, s36, 1.0
	v_pk_mul_f32 v[238:239], v[166:167], v[166:167]
	v_pk_mul_f32 v[244:245], v[136:137], v[136:137]
	v_rcp_f32_e32 v234, v234
	v_rcp_f32_e32 v240, v240
	v_rcp_f32_e32 v235, v235
	v_rcp_f32_e32 v241, v241
	v_pk_mul_f32 v[238:239], v[238:239], s[58:59] op_sel_hi:[1,0]
	v_pk_mul_f32 v[244:245], v[244:245], s[58:59] op_sel_hi:[1,0]
	v_pk_fma_f32 v[236:237], v[234:235], s[38:39], v[232:233] op_sel_hi:[1,0,0]
	v_pk_fma_f32 v[242:243], v[240:241], s[38:39], v[232:233] op_sel_hi:[1,0,0]
	v_exp_f32_e32 v238, v238
	v_exp_f32_e32 v244, v244
	v_pk_fma_f32 v[236:237], v[234:235], v[236:237], s[52:53] op_sel_hi:[1,1,0]
	v_pk_fma_f32 v[242:243], v[240:241], v[242:243], s[52:53] op_sel_hi:[1,1,0]
	v_exp_f32_e32 v239, v239
	v_exp_f32_e32 v245, v245
	v_pk_fma_f32 v[236:237], v[234:235], v[236:237], s[54:55] op_sel_hi:[1,1,0]
	v_pk_fma_f32 v[242:243], v[240:241], v[242:243], s[54:55] op_sel_hi:[1,1,0]
	v_pk_fma_f32 v[236:237], v[234:235], v[236:237], s[56:57] op_sel_hi:[1,1,0]
	v_pk_fma_f32 v[242:243], v[240:241], v[242:243], s[56:57] op_sel_hi:[1,1,0]
	v_pk_mul_f32 v[236:237], v[234:235], v[236:237]
	v_pk_mul_f32 v[242:243], v[240:241], v[242:243]
	v_pk_mul_f32 v[236:237], v[236:237], v[238:239]
	v_pk_mul_f32 v[242:243], v[242:243], v[244:245]
	v_max_f32_e32 v234, 0, v166
	v_max_f32_e32 v240, 0, v136
	v_max_f32_e32 v235, 0, v167
	v_max_f32_e32 v241, 0, v137
	v_fma_f32 v134, -|v166|, v236, v234
	v_fma_f32 v164, -|v136|, v242, v240
	v_fma_f32 v135, -|v167|, v237, v235
	v_fma_f32 v165, -|v137|, v243, v241
	v_fma_f32 v246, |v130|, s36, 1.0
	v_fma_f32 v254, |v132|, s36, 1.0
	v_fma_f32 v247, |v131|, s36, 1.0
	v_fma_f32 v255, |v133|, s36, 1.0
	v_pk_mul_f32 v[244:245], v[130:131], v[130:131]
	v_pk_mul_f32 v[238:239], v[132:133], v[132:133]
	v_rcp_f32_e32 v246, v246
	v_rcp_f32_e32 v254, v254
	v_rcp_f32_e32 v247, v247
	v_rcp_f32_e32 v255, v255
	v_pk_mul_f32 v[244:245], v[244:245], s[58:59] op_sel_hi:[1,0]
	v_pk_mul_f32 v[238:239], v[238:239], s[58:59] op_sel_hi:[1,0]
	v_pk_fma_f32 v[242:243], v[246:247], s[38:39], v[232:233] op_sel_hi:[1,0,0]
	v_pk_fma_f32 v[236:237], v[254:255], s[38:39], v[232:233] op_sel_hi:[1,0,0]
	v_exp_f32_e32 v244, v244
	v_exp_f32_e32 v238, v238
	v_pk_fma_f32 v[242:243], v[246:247], v[242:243], s[52:53] op_sel_hi:[1,1,0]
	v_pk_fma_f32 v[236:237], v[254:255], v[236:237], s[52:53] op_sel_hi:[1,1,0]
	v_exp_f32_e32 v245, v245
	v_exp_f32_e32 v239, v239
	v_pk_fma_f32 v[242:243], v[246:247], v[242:243], s[54:55] op_sel_hi:[1,1,0]
	v_pk_fma_f32 v[236:237], v[254:255], v[236:237], s[54:55] op_sel_hi:[1,1,0]
	v_pk_fma_f32 v[242:243], v[246:247], v[242:243], s[56:57] op_sel_hi:[1,1,0]
	v_pk_fma_f32 v[236:237], v[254:255], v[236:237], s[56:57] op_sel_hi:[1,1,0]
	v_pk_mul_f32 v[242:243], v[246:247], v[242:243]
	v_pk_mul_f32 v[236:237], v[254:255], v[236:237]
	v_pk_mul_f32 v[242:243], v[242:243], v[244:245]
	v_pk_mul_f32 v[236:237], v[236:237], v[238:239]
	v_max_f32_e32 v246, 0, v130
	v_max_f32_e32 v254, 0, v132
	v_max_f32_e32 v247, 0, v131
	v_max_f32_e32 v255, 0, v133
	v_fma_f32 v168, -|v130|, v242, v246
	v_fma_f32 v170, -|v132|, v236, v254
	v_fma_f32 v169, -|v131|, v243, v247
	v_fma_f32 v171, -|v133|, v237, v255
	v_cndmask_b32_e64 v130, 0, 1, s[40:41]
	v_cmp_ne_u32_e64 s[8:9], 1, v130
	s_andn2_b64 vcc, exec, s[40:41]
	s_cbranch_vccz .LBB0_236
	s_branch .LBB0_237

.LBB0_263:
	v_mov_b64_e32 v[232:233], s[50:51]
	v_fma_f32 v234, |v126|, s36, 1.0
	v_fma_f32 v240, |v132|, s36, 1.0
	v_fma_f32 v235, |v127|, s36, 1.0
	v_fma_f32 v241, |v133|, s36, 1.0
	v_pk_mul_f32 v[238:239], v[126:127], v[126:127]
	v_pk_mul_f32 v[244:245], v[132:133], v[132:133]
	v_rcp_f32_e32 v234, v234
	v_rcp_f32_e32 v240, v240
	v_rcp_f32_e32 v235, v235
	v_rcp_f32_e32 v241, v241
	v_pk_mul_f32 v[238:239], v[238:239], s[58:59] op_sel_hi:[1,0]
	v_pk_mul_f32 v[244:245], v[244:245], s[58:59] op_sel_hi:[1,0]
	v_pk_fma_f32 v[236:237], v[234:235], s[38:39], v[232:233] op_sel_hi:[1,0,0]
	v_pk_fma_f32 v[242:243], v[240:241], s[38:39], v[232:233] op_sel_hi:[1,0,0]
	v_exp_f32_e32 v238, v238
	v_exp_f32_e32 v244, v244
	v_pk_fma_f32 v[236:237], v[234:235], v[236:237], s[52:53] op_sel_hi:[1,1,0]
	v_pk_fma_f32 v[242:243], v[240:241], v[242:243], s[52:53] op_sel_hi:[1,1,0]
	v_exp_f32_e32 v239, v239
	v_exp_f32_e32 v245, v245
	v_pk_fma_f32 v[236:237], v[234:235], v[236:237], s[54:55] op_sel_hi:[1,1,0]
	v_pk_fma_f32 v[242:243], v[240:241], v[242:243], s[54:55] op_sel_hi:[1,1,0]
	v_pk_fma_f32 v[236:237], v[234:235], v[236:237], s[56:57] op_sel_hi:[1,1,0]
	v_pk_fma_f32 v[242:243], v[240:241], v[242:243], s[56:57] op_sel_hi:[1,1,0]
	v_pk_mul_f32 v[236:237], v[234:235], v[236:237]
	v_pk_mul_f32 v[242:243], v[240:241], v[242:243]
	v_pk_mul_f32 v[236:237], v[236:237], v[238:239]
	v_pk_mul_f32 v[242:243], v[242:243], v[244:245]
	v_max_f32_e32 v234, 0, v126
	v_max_f32_e32 v240, 0, v132
	v_max_f32_e32 v235, 0, v127
	v_max_f32_e32 v241, 0, v133
	v_fma_f32 v128, -|v126|, v236, v234
	v_fma_f32 v130, -|v132|, v242, v240
	v_fma_f32 v129, -|v127|, v237, v235
	v_fma_f32 v131, -|v133|, v243, v241
	v_fma_f32 v246, |v122|, s36, 1.0
	v_fma_f32 v254, |v124|, s36, 1.0
	v_fma_f32 v247, |v123|, s36, 1.0
	v_fma_f32 v255, |v125|, s36, 1.0
	v_pk_mul_f32 v[244:245], v[122:123], v[122:123]
	v_pk_mul_f32 v[238:239], v[124:125], v[124:125]
	v_rcp_f32_e32 v246, v246
	v_rcp_f32_e32 v254, v254
	v_rcp_f32_e32 v247, v247
	v_rcp_f32_e32 v255, v255
	v_pk_mul_f32 v[244:245], v[244:245], s[58:59] op_sel_hi:[1,0]
	v_pk_mul_f32 v[238:239], v[238:239], s[58:59] op_sel_hi:[1,0]
	v_pk_fma_f32 v[242:243], v[246:247], s[38:39], v[232:233] op_sel_hi:[1,0,0]
	v_pk_fma_f32 v[236:237], v[254:255], s[38:39], v[232:233] op_sel_hi:[1,0,0]
	v_exp_f32_e32 v244, v244
	v_exp_f32_e32 v238, v238
	v_pk_fma_f32 v[242:243], v[246:247], v[242:243], s[52:53] op_sel_hi:[1,1,0]
	v_pk_fma_f32 v[236:237], v[254:255], v[236:237], s[52:53] op_sel_hi:[1,1,0]
	v_exp_f32_e32 v245, v245
	v_exp_f32_e32 v239, v239
	v_pk_fma_f32 v[242:243], v[246:247], v[242:243], s[54:55] op_sel_hi:[1,1,0]
	v_pk_fma_f32 v[236:237], v[254:255], v[236:237], s[54:55] op_sel_hi:[1,1,0]
	v_pk_fma_f32 v[242:243], v[246:247], v[242:243], s[56:57] op_sel_hi:[1,1,0]
	v_pk_fma_f32 v[236:237], v[254:255], v[236:237], s[56:57] op_sel_hi:[1,1,0]
	v_pk_mul_f32 v[242:243], v[246:247], v[242:243]
	v_pk_mul_f32 v[236:237], v[254:255], v[236:237]
	v_pk_mul_f32 v[242:243], v[242:243], v[244:245]
	v_pk_mul_f32 v[236:237], v[236:237], v[238:239]
	v_max_f32_e32 v246, 0, v122
	v_max_f32_e32 v254, 0, v124
	v_max_f32_e32 v247, 0, v123
	v_max_f32_e32 v255, 0, v125
	v_fma_f32 v134, -|v122|, v242, v246
	v_fma_f32 v136, -|v124|, v236, v254
	v_fma_f32 v135, -|v123|, v243, v247
	v_fma_f32 v137, -|v125|, v237, v255
	v_cndmask_b32_e64 v122, 0, 1, s[0:1]
	v_cmp_ne_u32_e64 s[10:11], 1, v122
	s_andn2_b64 vcc, exec, s[0:1]
	s_cbranch_vccz .LBB0_244

.LBB0_287:
	v_mov_b64_e32 v[232:233], s[50:51]
	v_fma_f32 v234, |v130|, s36, 1.0
	v_fma_f32 v240, |v120|, s36, 1.0
	v_fma_f32 v235, |v131|, s36, 1.0
	v_fma_f32 v241, |v121|, s36, 1.0
	v_pk_mul_f32 v[238:239], v[130:131], v[130:131]
	v_pk_mul_f32 v[244:245], v[120:121], v[120:121]
	v_rcp_f32_e32 v234, v234
	v_rcp_f32_e32 v240, v240
	v_rcp_f32_e32 v235, v235
	v_rcp_f32_e32 v241, v241
	v_pk_mul_f32 v[238:239], v[238:239], s[58:59] op_sel_hi:[1,0]
	v_pk_mul_f32 v[244:245], v[244:245], s[58:59] op_sel_hi:[1,0]
	v_pk_fma_f32 v[236:237], v[234:235], s[38:39], v[232:233] op_sel_hi:[1,0,0]
	v_pk_fma_f32 v[242:243], v[240:241], s[38:39], v[232:233] op_sel_hi:[1,0,0]
	v_exp_f32_e32 v238, v238
	v_exp_f32_e32 v244, v244
	v_pk_fma_f32 v[236:237], v[234:235], v[236:237], s[52:53] op_sel_hi:[1,1,0]
	v_pk_fma_f32 v[242:243], v[240:241], v[242:243], s[52:53] op_sel_hi:[1,1,0]
	v_exp_f32_e32 v239, v239
	v_exp_f32_e32 v245, v245
	v_pk_fma_f32 v[236:237], v[234:235], v[236:237], s[54:55] op_sel_hi:[1,1,0]
	v_pk_fma_f32 v[242:243], v[240:241], v[242:243], s[54:55] op_sel_hi:[1,1,0]
	v_pk_fma_f32 v[236:237], v[234:235], v[236:237], s[56:57] op_sel_hi:[1,1,0]
	v_pk_fma_f32 v[242:243], v[240:241], v[242:243], s[56:57] op_sel_hi:[1,1,0]
	v_pk_mul_f32 v[236:237], v[234:235], v[236:237]
	v_pk_mul_f32 v[242:243], v[240:241], v[242:243]
	v_pk_mul_f32 v[236:237], v[236:237], v[238:239]
	v_pk_mul_f32 v[242:243], v[242:243], v[244:245]
	v_max_f32_e32 v234, 0, v130
	v_max_f32_e32 v240, 0, v120
	v_max_f32_e32 v235, 0, v131
	v_max_f32_e32 v241, 0, v121
	v_fma_f32 v118, -|v130|, v236, v234
	v_fma_f32 v128, -|v120|, v242, v240
	v_fma_f32 v119, -|v131|, v237, v235
	v_fma_f32 v129, -|v121|, v243, v241
	v_fma_f32 v246, |v114|, s36, 1.0
	v_fma_f32 v254, |v116|, s36, 1.0
	v_fma_f32 v247, |v115|, s36, 1.0
	v_fma_f32 v255, |v117|, s36, 1.0
	v_pk_mul_f32 v[244:245], v[114:115], v[114:115]
	v_pk_mul_f32 v[238:239], v[116:117], v[116:117]
	v_rcp_f32_e32 v246, v246
	v_rcp_f32_e32 v254, v254
	v_rcp_f32_e32 v247, v247
	v_rcp_f32_e32 v255, v255
	v_pk_mul_f32 v[244:245], v[244:245], s[58:59] op_sel_hi:[1,0]
	v_pk_mul_f32 v[238:239], v[238:239], s[58:59] op_sel_hi:[1,0]
	v_pk_fma_f32 v[242:243], v[246:247], s[38:39], v[232:233] op_sel_hi:[1,0,0]
	v_pk_fma_f32 v[236:237], v[254:255], s[38:39], v[232:233] op_sel_hi:[1,0,0]
	v_exp_f32_e32 v244, v244
	v_exp_f32_e32 v238, v238
	v_pk_fma_f32 v[242:243], v[246:247], v[242:243], s[52:53] op_sel_hi:[1,1,0]
	v_pk_fma_f32 v[236:237], v[254:255], v[236:237], s[52:53] op_sel_hi:[1,1,0]
	v_exp_f32_e32 v245, v245
	v_exp_f32_e32 v239, v239
	v_pk_fma_f32 v[242:243], v[246:247], v[242:243], s[54:55] op_sel_hi:[1,1,0]
	v_pk_fma_f32 v[236:237], v[254:255], v[236:237], s[54:55] op_sel_hi:[1,1,0]
	v_pk_fma_f32 v[242:243], v[246:247], v[242:243], s[56:57] op_sel_hi:[1,1,0]
	v_pk_fma_f32 v[236:237], v[254:255], v[236:237], s[56:57] op_sel_hi:[1,1,0]
	v_pk_mul_f32 v[242:243], v[246:247], v[242:243]
	v_pk_mul_f32 v[236:237], v[254:255], v[236:237]
	v_pk_mul_f32 v[242:243], v[242:243], v[244:245]
	v_pk_mul_f32 v[236:237], v[236:237], v[238:239]
	v_max_f32_e32 v246, 0, v114
	v_max_f32_e32 v254, 0, v116
	v_max_f32_e32 v247, 0, v115
	v_max_f32_e32 v255, 0, v117
	v_fma_f32 v132, -|v114|, v242, v246
	v_fma_f32 v134, -|v116|, v236, v254
	v_fma_f32 v133, -|v115|, v243, v247
	v_fma_f32 v135, -|v117|, v237, v255
	s_and_b64 vcc, exec, s[8:9]
	s_cbranch_vccz .LBB0_269
	s_branch .LBB0_270

.LBB0_296:
	v_mov_b64_e32 v[232:233], s[50:51]
	v_fma_f32 v234, |v110|, s36, 1.0
	v_fma_f32 v240, |v116|, s36, 1.0
	v_fma_f32 v235, |v111|, s36, 1.0
	v_fma_f32 v241, |v117|, s36, 1.0
	v_pk_mul_f32 v[238:239], v[110:111], v[110:111]
	v_pk_mul_f32 v[244:245], v[116:117], v[116:117]
	v_rcp_f32_e32 v234, v234
	v_rcp_f32_e32 v240, v240
	v_rcp_f32_e32 v235, v235
	v_rcp_f32_e32 v241, v241
	v_pk_mul_f32 v[238:239], v[238:239], s[58:59] op_sel_hi:[1,0]
	v_pk_mul_f32 v[244:245], v[244:245], s[58:59] op_sel_hi:[1,0]
	v_pk_fma_f32 v[236:237], v[234:235], s[38:39], v[232:233] op_sel_hi:[1,0,0]
	v_pk_fma_f32 v[242:243], v[240:241], s[38:39], v[232:233] op_sel_hi:[1,0,0]
	v_exp_f32_e32 v238, v238
	v_exp_f32_e32 v244, v244
	v_pk_fma_f32 v[236:237], v[234:235], v[236:237], s[52:53] op_sel_hi:[1,1,0]
	v_pk_fma_f32 v[242:243], v[240:241], v[242:243], s[52:53] op_sel_hi:[1,1,0]
	v_exp_f32_e32 v239, v239
	v_exp_f32_e32 v245, v245
	v_pk_fma_f32 v[236:237], v[234:235], v[236:237], s[54:55] op_sel_hi:[1,1,0]
	v_pk_fma_f32 v[242:243], v[240:241], v[242:243], s[54:55] op_sel_hi:[1,1,0]
	v_pk_fma_f32 v[236:237], v[234:235], v[236:237], s[56:57] op_sel_hi:[1,1,0]
	v_pk_fma_f32 v[242:243], v[240:241], v[242:243], s[56:57] op_sel_hi:[1,1,0]
	v_pk_mul_f32 v[236:237], v[234:235], v[236:237]
	v_pk_mul_f32 v[242:243], v[240:241], v[242:243]
	v_pk_mul_f32 v[236:237], v[236:237], v[238:239]
	v_pk_mul_f32 v[242:243], v[242:243], v[244:245]
	v_max_f32_e32 v234, 0, v110
	v_max_f32_e32 v240, 0, v116
	v_max_f32_e32 v235, 0, v111
	v_max_f32_e32 v241, 0, v117
	v_fma_f32 v112, -|v110|, v236, v234
	v_fma_f32 v114, -|v116|, v242, v240
	v_fma_f32 v113, -|v111|, v237, v235
	v_fma_f32 v115, -|v117|, v243, v241
	v_fma_f32 v246, |v106|, s36, 1.0
	v_fma_f32 v254, |v108|, s36, 1.0
	v_fma_f32 v247, |v107|, s36, 1.0
	v_fma_f32 v255, |v109|, s36, 1.0
	v_pk_mul_f32 v[244:245], v[106:107], v[106:107]
	v_pk_mul_f32 v[238:239], v[108:109], v[108:109]
	v_rcp_f32_e32 v246, v246
	v_rcp_f32_e32 v254, v254
	v_rcp_f32_e32 v247, v247
	v_rcp_f32_e32 v255, v255
	v_pk_mul_f32 v[244:245], v[244:245], s[58:59] op_sel_hi:[1,0]
	v_pk_mul_f32 v[238:239], v[238:239], s[58:59] op_sel_hi:[1,0]
	v_pk_fma_f32 v[242:243], v[246:247], s[38:39], v[232:233] op_sel_hi:[1,0,0]
	v_pk_fma_f32 v[236:237], v[254:255], s[38:39], v[232:233] op_sel_hi:[1,0,0]
	v_exp_f32_e32 v244, v244
	v_exp_f32_e32 v238, v238
	v_pk_fma_f32 v[242:243], v[246:247], v[242:243], s[52:53] op_sel_hi:[1,1,0]
	v_pk_fma_f32 v[236:237], v[254:255], v[236:237], s[52:53] op_sel_hi:[1,1,0]
	v_exp_f32_e32 v245, v245
	v_exp_f32_e32 v239, v239
	v_pk_fma_f32 v[242:243], v[246:247], v[242:243], s[54:55] op_sel_hi:[1,1,0]
	v_pk_fma_f32 v[236:237], v[254:255], v[236:237], s[54:55] op_sel_hi:[1,1,0]
	v_pk_fma_f32 v[242:243], v[246:247], v[242:243], s[56:57] op_sel_hi:[1,1,0]
	v_pk_fma_f32 v[236:237], v[254:255], v[236:237], s[56:57] op_sel_hi:[1,1,0]
	v_pk_mul_f32 v[242:243], v[246:247], v[242:243]
	v_pk_mul_f32 v[236:237], v[254:255], v[236:237]
	v_pk_mul_f32 v[242:243], v[242:243], v[244:245]
	v_pk_mul_f32 v[236:237], v[236:237], v[238:239]
	v_max_f32_e32 v246, 0, v106
	v_max_f32_e32 v254, 0, v108
	v_max_f32_e32 v247, 0, v107
	v_max_f32_e32 v255, 0, v109
	v_fma_f32 v118, -|v106|, v242, v246
	v_fma_f32 v120, -|v108|, v236, v254
	v_fma_f32 v119, -|v107|, v243, v247
	v_fma_f32 v121, -|v109|, v237, v255
	s_and_b64 vcc, exec, s[10:11]
	s_cbranch_vccz .LBB0_277

.LBB0_320:
	v_mov_b64_e32 v[232:233], s[50:51]
	v_fma_f32 v234, |v114|, s36, 1.0
	v_fma_f32 v240, |v104|, s36, 1.0
	v_fma_f32 v235, |v115|, s36, 1.0
	v_fma_f32 v241, |v105|, s36, 1.0
	v_pk_mul_f32 v[238:239], v[114:115], v[114:115]
	v_pk_mul_f32 v[244:245], v[104:105], v[104:105]
	v_rcp_f32_e32 v234, v234
	v_rcp_f32_e32 v240, v240
	v_rcp_f32_e32 v235, v235
	v_rcp_f32_e32 v241, v241
	v_pk_mul_f32 v[238:239], v[238:239], s[58:59] op_sel_hi:[1,0]
	v_pk_mul_f32 v[244:245], v[244:245], s[58:59] op_sel_hi:[1,0]
	v_pk_fma_f32 v[236:237], v[234:235], s[38:39], v[232:233] op_sel_hi:[1,0,0]
	v_pk_fma_f32 v[242:243], v[240:241], s[38:39], v[232:233] op_sel_hi:[1,0,0]
	v_exp_f32_e32 v238, v238
	v_exp_f32_e32 v244, v244
	v_pk_fma_f32 v[236:237], v[234:235], v[236:237], s[52:53] op_sel_hi:[1,1,0]
	v_pk_fma_f32 v[242:243], v[240:241], v[242:243], s[52:53] op_sel_hi:[1,1,0]
	v_exp_f32_e32 v239, v239
	v_exp_f32_e32 v245, v245
	v_pk_fma_f32 v[236:237], v[234:235], v[236:237], s[54:55] op_sel_hi:[1,1,0]
	v_pk_fma_f32 v[242:243], v[240:241], v[242:243], s[54:55] op_sel_hi:[1,1,0]
	v_pk_fma_f32 v[236:237], v[234:235], v[236:237], s[56:57] op_sel_hi:[1,1,0]
	v_pk_fma_f32 v[242:243], v[240:241], v[242:243], s[56:57] op_sel_hi:[1,1,0]
	v_pk_mul_f32 v[236:237], v[234:235], v[236:237]
	v_pk_mul_f32 v[242:243], v[240:241], v[242:243]
	v_pk_mul_f32 v[236:237], v[236:237], v[238:239]
	v_pk_mul_f32 v[242:243], v[242:243], v[244:245]
	v_max_f32_e32 v234, 0, v114
	v_max_f32_e32 v240, 0, v104
	v_max_f32_e32 v235, 0, v115
	v_max_f32_e32 v241, 0, v105
	v_fma_f32 v102, -|v114|, v236, v234
	v_fma_f32 v112, -|v104|, v242, v240
	v_fma_f32 v103, -|v115|, v237, v235
	v_fma_f32 v113, -|v105|, v243, v241
	v_fma_f32 v246, |v98|, s36, 1.0
	v_fma_f32 v254, |v100|, s36, 1.0
	v_fma_f32 v247, |v99|, s36, 1.0
	v_fma_f32 v255, |v101|, s36, 1.0
	v_pk_mul_f32 v[244:245], v[98:99], v[98:99]
	v_pk_mul_f32 v[238:239], v[100:101], v[100:101]
	v_rcp_f32_e32 v246, v246
	v_rcp_f32_e32 v254, v254
	v_rcp_f32_e32 v247, v247
	v_rcp_f32_e32 v255, v255
	v_pk_mul_f32 v[244:245], v[244:245], s[58:59] op_sel_hi:[1,0]
	v_pk_mul_f32 v[238:239], v[238:239], s[58:59] op_sel_hi:[1,0]
	v_pk_fma_f32 v[242:243], v[246:247], s[38:39], v[232:233] op_sel_hi:[1,0,0]
	v_pk_fma_f32 v[236:237], v[254:255], s[38:39], v[232:233] op_sel_hi:[1,0,0]
	v_exp_f32_e32 v244, v244
	v_exp_f32_e32 v238, v238
	v_pk_fma_f32 v[242:243], v[246:247], v[242:243], s[52:53] op_sel_hi:[1,1,0]
	v_pk_fma_f32 v[236:237], v[254:255], v[236:237], s[52:53] op_sel_hi:[1,1,0]
	v_exp_f32_e32 v245, v245
	v_exp_f32_e32 v239, v239
	v_pk_fma_f32 v[242:243], v[246:247], v[242:243], s[54:55] op_sel_hi:[1,1,0]
	v_pk_fma_f32 v[236:237], v[254:255], v[236:237], s[54:55] op_sel_hi:[1,1,0]
	v_pk_fma_f32 v[242:243], v[246:247], v[242:243], s[56:57] op_sel_hi:[1,1,0]
	v_pk_fma_f32 v[236:237], v[254:255], v[236:237], s[56:57] op_sel_hi:[1,1,0]
	v_pk_mul_f32 v[242:243], v[246:247], v[242:243]
	v_pk_mul_f32 v[236:237], v[254:255], v[236:237]
	v_pk_mul_f32 v[242:243], v[242:243], v[244:245]
	v_pk_mul_f32 v[236:237], v[236:237], v[238:239]
	v_max_f32_e32 v246, 0, v98
	v_max_f32_e32 v254, 0, v100
	v_max_f32_e32 v247, 0, v99
	v_max_f32_e32 v255, 0, v101
	v_fma_f32 v116, -|v98|, v242, v246
	v_fma_f32 v118, -|v100|, v236, v254
	v_fma_f32 v117, -|v99|, v243, v247
	v_fma_f32 v119, -|v101|, v237, v255
	s_and_b64 vcc, exec, s[8:9]
	s_cbranch_vccz .LBB0_302
	s_branch .LBB0_303

.LBB0_329:
	v_mov_b64_e32 v[232:233], s[50:51]
	v_fma_f32 v234, |v94|, s36, 1.0
	v_fma_f32 v240, |v100|, s36, 1.0
	v_fma_f32 v235, |v95|, s36, 1.0
	v_fma_f32 v241, |v101|, s36, 1.0
	v_pk_mul_f32 v[238:239], v[94:95], v[94:95]
	v_pk_mul_f32 v[244:245], v[100:101], v[100:101]
	v_rcp_f32_e32 v234, v234
	v_rcp_f32_e32 v240, v240
	v_rcp_f32_e32 v235, v235
	v_rcp_f32_e32 v241, v241
	v_pk_mul_f32 v[238:239], v[238:239], s[58:59] op_sel_hi:[1,0]
	v_pk_mul_f32 v[244:245], v[244:245], s[58:59] op_sel_hi:[1,0]
	v_pk_fma_f32 v[236:237], v[234:235], s[38:39], v[232:233] op_sel_hi:[1,0,0]
	v_pk_fma_f32 v[242:243], v[240:241], s[38:39], v[232:233] op_sel_hi:[1,0,0]
	v_exp_f32_e32 v238, v238
	v_exp_f32_e32 v244, v244
	v_pk_fma_f32 v[236:237], v[234:235], v[236:237], s[52:53] op_sel_hi:[1,1,0]
	v_pk_fma_f32 v[242:243], v[240:241], v[242:243], s[52:53] op_sel_hi:[1,1,0]
	v_exp_f32_e32 v239, v239
	v_exp_f32_e32 v245, v245
	v_pk_fma_f32 v[236:237], v[234:235], v[236:237], s[54:55] op_sel_hi:[1,1,0]
	v_pk_fma_f32 v[242:243], v[240:241], v[242:243], s[54:55] op_sel_hi:[1,1,0]
	v_pk_fma_f32 v[236:237], v[234:235], v[236:237], s[56:57] op_sel_hi:[1,1,0]
	v_pk_fma_f32 v[242:243], v[240:241], v[242:243], s[56:57] op_sel_hi:[1,1,0]
	v_pk_mul_f32 v[236:237], v[234:235], v[236:237]
	v_pk_mul_f32 v[242:243], v[240:241], v[242:243]
	v_pk_mul_f32 v[236:237], v[236:237], v[238:239]
	v_pk_mul_f32 v[242:243], v[242:243], v[244:245]
	v_max_f32_e32 v234, 0, v94
	v_max_f32_e32 v240, 0, v100
	v_max_f32_e32 v235, 0, v95
	v_max_f32_e32 v241, 0, v101
	v_fma_f32 v96, -|v94|, v236, v234
	v_fma_f32 v98, -|v100|, v242, v240
	v_fma_f32 v97, -|v95|, v237, v235
	v_fma_f32 v99, -|v101|, v243, v241
	v_fma_f32 v246, |v90|, s36, 1.0
	v_fma_f32 v254, |v92|, s36, 1.0
	v_fma_f32 v247, |v91|, s36, 1.0
	v_fma_f32 v255, |v93|, s36, 1.0
	v_pk_mul_f32 v[244:245], v[90:91], v[90:91]
	v_pk_mul_f32 v[238:239], v[92:93], v[92:93]
	v_rcp_f32_e32 v246, v246
	v_rcp_f32_e32 v254, v254
	v_rcp_f32_e32 v247, v247
	v_rcp_f32_e32 v255, v255
	v_pk_mul_f32 v[244:245], v[244:245], s[58:59] op_sel_hi:[1,0]
	v_pk_mul_f32 v[238:239], v[238:239], s[58:59] op_sel_hi:[1,0]
	v_pk_fma_f32 v[242:243], v[246:247], s[38:39], v[232:233] op_sel_hi:[1,0,0]
	v_pk_fma_f32 v[236:237], v[254:255], s[38:39], v[232:233] op_sel_hi:[1,0,0]
	v_exp_f32_e32 v244, v244
	v_exp_f32_e32 v238, v238
	v_pk_fma_f32 v[242:243], v[246:247], v[242:243], s[52:53] op_sel_hi:[1,1,0]
	v_pk_fma_f32 v[236:237], v[254:255], v[236:237], s[52:53] op_sel_hi:[1,1,0]
	v_exp_f32_e32 v245, v245
	v_exp_f32_e32 v239, v239
	v_pk_fma_f32 v[242:243], v[246:247], v[242:243], s[54:55] op_sel_hi:[1,1,0]
	v_pk_fma_f32 v[236:237], v[254:255], v[236:237], s[54:55] op_sel_hi:[1,1,0]
	v_pk_fma_f32 v[242:243], v[246:247], v[242:243], s[56:57] op_sel_hi:[1,1,0]
	v_pk_fma_f32 v[236:237], v[254:255], v[236:237], s[56:57] op_sel_hi:[1,1,0]
	v_pk_mul_f32 v[242:243], v[246:247], v[242:243]
	v_pk_mul_f32 v[236:237], v[254:255], v[236:237]
	v_pk_mul_f32 v[242:243], v[242:243], v[244:245]
	v_pk_mul_f32 v[236:237], v[236:237], v[238:239]
	v_max_f32_e32 v246, 0, v90
	v_max_f32_e32 v254, 0, v92
	v_max_f32_e32 v247, 0, v91
	v_max_f32_e32 v255, 0, v93
	v_fma_f32 v102, -|v90|, v242, v246
	v_fma_f32 v104, -|v92|, v236, v254
	v_fma_f32 v103, -|v91|, v243, v247
	v_fma_f32 v105, -|v93|, v237, v255
	s_and_b64 vcc, exec, s[10:11]
	s_cbranch_vccz .LBB0_310

.LBB0_353:
	v_mov_b64_e32 v[232:233], s[50:51]
	v_fma_f32 v234, |v98|, s36, 1.0
	v_fma_f32 v240, |v88|, s36, 1.0
	v_fma_f32 v235, |v99|, s36, 1.0
	v_fma_f32 v241, |v89|, s36, 1.0
	v_pk_mul_f32 v[238:239], v[98:99], v[98:99]
	v_pk_mul_f32 v[244:245], v[88:89], v[88:89]
	v_rcp_f32_e32 v234, v234
	v_rcp_f32_e32 v240, v240
	v_rcp_f32_e32 v235, v235
	v_rcp_f32_e32 v241, v241
	v_pk_mul_f32 v[238:239], v[238:239], s[58:59] op_sel_hi:[1,0]
	v_pk_mul_f32 v[244:245], v[244:245], s[58:59] op_sel_hi:[1,0]
	v_pk_fma_f32 v[236:237], v[234:235], s[38:39], v[232:233] op_sel_hi:[1,0,0]
	v_pk_fma_f32 v[242:243], v[240:241], s[38:39], v[232:233] op_sel_hi:[1,0,0]
	v_exp_f32_e32 v238, v238
	v_exp_f32_e32 v244, v244
	v_pk_fma_f32 v[236:237], v[234:235], v[236:237], s[52:53] op_sel_hi:[1,1,0]
	v_pk_fma_f32 v[242:243], v[240:241], v[242:243], s[52:53] op_sel_hi:[1,1,0]
	v_exp_f32_e32 v239, v239
	v_exp_f32_e32 v245, v245
	v_pk_fma_f32 v[236:237], v[234:235], v[236:237], s[54:55] op_sel_hi:[1,1,0]
	v_pk_fma_f32 v[242:243], v[240:241], v[242:243], s[54:55] op_sel_hi:[1,1,0]
	v_pk_fma_f32 v[236:237], v[234:235], v[236:237], s[56:57] op_sel_hi:[1,1,0]
	v_pk_fma_f32 v[242:243], v[240:241], v[242:243], s[56:57] op_sel_hi:[1,1,0]
	v_pk_mul_f32 v[236:237], v[234:235], v[236:237]
	v_pk_mul_f32 v[242:243], v[240:241], v[242:243]
	v_pk_mul_f32 v[236:237], v[236:237], v[238:239]
	v_pk_mul_f32 v[242:243], v[242:243], v[244:245]
	v_max_f32_e32 v234, 0, v98
	v_max_f32_e32 v240, 0, v88
	v_max_f32_e32 v235, 0, v99
	v_max_f32_e32 v241, 0, v89
	v_fma_f32 v86, -|v98|, v236, v234
	v_fma_f32 v96, -|v88|, v242, v240
	v_fma_f32 v87, -|v99|, v237, v235
	v_fma_f32 v97, -|v89|, v243, v241
	v_fma_f32 v246, |v82|, s36, 1.0
	v_fma_f32 v254, |v84|, s36, 1.0
	v_fma_f32 v247, |v83|, s36, 1.0
	v_fma_f32 v255, |v85|, s36, 1.0
	v_pk_mul_f32 v[244:245], v[82:83], v[82:83]
	v_pk_mul_f32 v[238:239], v[84:85], v[84:85]
	v_rcp_f32_e32 v246, v246
	v_rcp_f32_e32 v254, v254
	v_rcp_f32_e32 v247, v247
	v_rcp_f32_e32 v255, v255
	v_pk_mul_f32 v[244:245], v[244:245], s[58:59] op_sel_hi:[1,0]
	v_pk_mul_f32 v[238:239], v[238:239], s[58:59] op_sel_hi:[1,0]
	v_pk_fma_f32 v[242:243], v[246:247], s[38:39], v[232:233] op_sel_hi:[1,0,0]
	v_pk_fma_f32 v[236:237], v[254:255], s[38:39], v[232:233] op_sel_hi:[1,0,0]
	v_exp_f32_e32 v244, v244
	v_exp_f32_e32 v238, v238
	v_pk_fma_f32 v[242:243], v[246:247], v[242:243], s[52:53] op_sel_hi:[1,1,0]
	v_pk_fma_f32 v[236:237], v[254:255], v[236:237], s[52:53] op_sel_hi:[1,1,0]
	v_exp_f32_e32 v245, v245
	v_exp_f32_e32 v239, v239
	v_pk_fma_f32 v[242:243], v[246:247], v[242:243], s[54:55] op_sel_hi:[1,1,0]
	v_pk_fma_f32 v[236:237], v[254:255], v[236:237], s[54:55] op_sel_hi:[1,1,0]
	v_pk_fma_f32 v[242:243], v[246:247], v[242:243], s[56:57] op_sel_hi:[1,1,0]
	v_pk_fma_f32 v[236:237], v[254:255], v[236:237], s[56:57] op_sel_hi:[1,1,0]
	v_pk_mul_f32 v[242:243], v[246:247], v[242:243]
	v_pk_mul_f32 v[236:237], v[254:255], v[236:237]
	v_pk_mul_f32 v[242:243], v[242:243], v[244:245]
	v_pk_mul_f32 v[236:237], v[236:237], v[238:239]
	v_max_f32_e32 v246, 0, v82
	v_max_f32_e32 v254, 0, v84
	v_max_f32_e32 v247, 0, v83
	v_max_f32_e32 v255, 0, v85
	v_fma_f32 v100, -|v82|, v242, v246
	v_fma_f32 v102, -|v84|, v236, v254
	v_fma_f32 v101, -|v83|, v243, v247
	v_fma_f32 v103, -|v85|, v237, v255
	s_and_b64 vcc, exec, s[8:9]
	s_cbranch_vccz .LBB0_335
	s_branch .LBB0_336

.LBB0_362:
	v_mov_b64_e32 v[232:233], s[50:51]
	v_fma_f32 v234, |v78|, s36, 1.0
	v_fma_f32 v240, |v84|, s36, 1.0
	v_fma_f32 v235, |v79|, s36, 1.0
	v_fma_f32 v241, |v85|, s36, 1.0
	v_pk_mul_f32 v[238:239], v[78:79], v[78:79]
	v_pk_mul_f32 v[244:245], v[84:85], v[84:85]
	v_rcp_f32_e32 v234, v234
	v_rcp_f32_e32 v240, v240
	v_rcp_f32_e32 v235, v235
	v_rcp_f32_e32 v241, v241
	v_pk_mul_f32 v[238:239], v[238:239], s[58:59] op_sel_hi:[1,0]
	v_pk_mul_f32 v[244:245], v[244:245], s[58:59] op_sel_hi:[1,0]
	v_pk_fma_f32 v[236:237], v[234:235], s[38:39], v[232:233] op_sel_hi:[1,0,0]
	v_pk_fma_f32 v[242:243], v[240:241], s[38:39], v[232:233] op_sel_hi:[1,0,0]
	v_exp_f32_e32 v238, v238
	v_exp_f32_e32 v244, v244
	v_pk_fma_f32 v[236:237], v[234:235], v[236:237], s[52:53] op_sel_hi:[1,1,0]
	v_pk_fma_f32 v[242:243], v[240:241], v[242:243], s[52:53] op_sel_hi:[1,1,0]
	v_exp_f32_e32 v239, v239
	v_exp_f32_e32 v245, v245
	v_pk_fma_f32 v[236:237], v[234:235], v[236:237], s[54:55] op_sel_hi:[1,1,0]
	v_pk_fma_f32 v[242:243], v[240:241], v[242:243], s[54:55] op_sel_hi:[1,1,0]
	v_pk_fma_f32 v[236:237], v[234:235], v[236:237], s[56:57] op_sel_hi:[1,1,0]
	v_pk_fma_f32 v[242:243], v[240:241], v[242:243], s[56:57] op_sel_hi:[1,1,0]
	v_pk_mul_f32 v[236:237], v[234:235], v[236:237]
	v_pk_mul_f32 v[242:243], v[240:241], v[242:243]
	v_pk_mul_f32 v[236:237], v[236:237], v[238:239]
	v_pk_mul_f32 v[242:243], v[242:243], v[244:245]
	v_max_f32_e32 v234, 0, v78
	v_max_f32_e32 v240, 0, v84
	v_max_f32_e32 v235, 0, v79
	v_max_f32_e32 v241, 0, v85
	v_fma_f32 v80, -|v78|, v236, v234
	v_fma_f32 v82, -|v84|, v242, v240
	v_fma_f32 v81, -|v79|, v237, v235
	v_fma_f32 v83, -|v85|, v243, v241
	v_fma_f32 v246, |v74|, s36, 1.0
	v_fma_f32 v254, |v76|, s36, 1.0
	v_fma_f32 v247, |v75|, s36, 1.0
	v_fma_f32 v255, |v77|, s36, 1.0
	v_pk_mul_f32 v[244:245], v[74:75], v[74:75]
	v_pk_mul_f32 v[238:239], v[76:77], v[76:77]
	v_rcp_f32_e32 v246, v246
	v_rcp_f32_e32 v254, v254
	v_rcp_f32_e32 v247, v247
	v_rcp_f32_e32 v255, v255
	v_pk_mul_f32 v[244:245], v[244:245], s[58:59] op_sel_hi:[1,0]
	v_pk_mul_f32 v[238:239], v[238:239], s[58:59] op_sel_hi:[1,0]
	v_pk_fma_f32 v[242:243], v[246:247], s[38:39], v[232:233] op_sel_hi:[1,0,0]
	v_pk_fma_f32 v[236:237], v[254:255], s[38:39], v[232:233] op_sel_hi:[1,0,0]
	v_exp_f32_e32 v244, v244
	v_exp_f32_e32 v238, v238
	v_pk_fma_f32 v[242:243], v[246:247], v[242:243], s[52:53] op_sel_hi:[1,1,0]
	v_pk_fma_f32 v[236:237], v[254:255], v[236:237], s[52:53] op_sel_hi:[1,1,0]
	v_exp_f32_e32 v245, v245
	v_exp_f32_e32 v239, v239
	v_pk_fma_f32 v[242:243], v[246:247], v[242:243], s[54:55] op_sel_hi:[1,1,0]
	v_pk_fma_f32 v[236:237], v[254:255], v[236:237], s[54:55] op_sel_hi:[1,1,0]
	v_pk_fma_f32 v[242:243], v[246:247], v[242:243], s[56:57] op_sel_hi:[1,1,0]
	v_pk_fma_f32 v[236:237], v[254:255], v[236:237], s[56:57] op_sel_hi:[1,1,0]
	v_pk_mul_f32 v[242:243], v[246:247], v[242:243]
	v_pk_mul_f32 v[236:237], v[254:255], v[236:237]
	v_pk_mul_f32 v[242:243], v[242:243], v[244:245]
	v_pk_mul_f32 v[236:237], v[236:237], v[238:239]
	v_max_f32_e32 v246, 0, v74
	v_max_f32_e32 v254, 0, v76
	v_max_f32_e32 v247, 0, v75
	v_max_f32_e32 v255, 0, v77
	v_fma_f32 v86, -|v74|, v242, v246
	v_fma_f32 v88, -|v76|, v236, v254
	v_fma_f32 v87, -|v75|, v243, v247
	v_fma_f32 v89, -|v77|, v237, v255
	s_and_b64 vcc, exec, s[10:11]
	s_cbranch_vccz .LBB0_343

.LBB0_386:
	v_mov_b64_e32 v[232:233], s[50:51]
	v_fma_f32 v234, |v82|, s36, 1.0
	v_fma_f32 v240, |v72|, s36, 1.0
	v_fma_f32 v235, |v83|, s36, 1.0
	v_fma_f32 v241, |v73|, s36, 1.0
	v_pk_mul_f32 v[238:239], v[82:83], v[82:83]
	v_pk_mul_f32 v[244:245], v[72:73], v[72:73]
	v_rcp_f32_e32 v234, v234
	v_rcp_f32_e32 v240, v240
	v_rcp_f32_e32 v235, v235
	v_rcp_f32_e32 v241, v241
	v_pk_mul_f32 v[238:239], v[238:239], s[58:59] op_sel_hi:[1,0]
	v_pk_mul_f32 v[244:245], v[244:245], s[58:59] op_sel_hi:[1,0]
	v_pk_fma_f32 v[236:237], v[234:235], s[38:39], v[232:233] op_sel_hi:[1,0,0]
	v_pk_fma_f32 v[242:243], v[240:241], s[38:39], v[232:233] op_sel_hi:[1,0,0]
	v_exp_f32_e32 v238, v238
	v_exp_f32_e32 v244, v244
	v_pk_fma_f32 v[236:237], v[234:235], v[236:237], s[52:53] op_sel_hi:[1,1,0]
	v_pk_fma_f32 v[242:243], v[240:241], v[242:243], s[52:53] op_sel_hi:[1,1,0]
	v_exp_f32_e32 v239, v239
	v_exp_f32_e32 v245, v245
	v_pk_fma_f32 v[236:237], v[234:235], v[236:237], s[54:55] op_sel_hi:[1,1,0]
	v_pk_fma_f32 v[242:243], v[240:241], v[242:243], s[54:55] op_sel_hi:[1,1,0]
	v_pk_fma_f32 v[236:237], v[234:235], v[236:237], s[56:57] op_sel_hi:[1,1,0]
	v_pk_fma_f32 v[242:243], v[240:241], v[242:243], s[56:57] op_sel_hi:[1,1,0]
	v_pk_mul_f32 v[236:237], v[234:235], v[236:237]
	v_pk_mul_f32 v[242:243], v[240:241], v[242:243]
	v_pk_mul_f32 v[236:237], v[236:237], v[238:239]
	v_pk_mul_f32 v[242:243], v[242:243], v[244:245]
	v_max_f32_e32 v234, 0, v82
	v_max_f32_e32 v240, 0, v72
	v_max_f32_e32 v235, 0, v83
	v_max_f32_e32 v241, 0, v73
	v_fma_f32 v70, -|v82|, v236, v234
	v_fma_f32 v80, -|v72|, v242, v240
	v_fma_f32 v71, -|v83|, v237, v235
	v_fma_f32 v81, -|v73|, v243, v241
	v_fma_f32 v246, |v66|, s36, 1.0
	v_fma_f32 v254, |v68|, s36, 1.0
	v_fma_f32 v247, |v67|, s36, 1.0
	v_fma_f32 v255, |v69|, s36, 1.0
	v_pk_mul_f32 v[244:245], v[66:67], v[66:67]
	v_pk_mul_f32 v[238:239], v[68:69], v[68:69]
	v_rcp_f32_e32 v246, v246
	v_rcp_f32_e32 v254, v254
	v_rcp_f32_e32 v247, v247
	v_rcp_f32_e32 v255, v255
	v_pk_mul_f32 v[244:245], v[244:245], s[58:59] op_sel_hi:[1,0]
	v_pk_mul_f32 v[238:239], v[238:239], s[58:59] op_sel_hi:[1,0]
	v_pk_fma_f32 v[242:243], v[246:247], s[38:39], v[232:233] op_sel_hi:[1,0,0]
	v_pk_fma_f32 v[236:237], v[254:255], s[38:39], v[232:233] op_sel_hi:[1,0,0]
	v_exp_f32_e32 v244, v244
	v_exp_f32_e32 v238, v238
	v_pk_fma_f32 v[242:243], v[246:247], v[242:243], s[52:53] op_sel_hi:[1,1,0]
	v_pk_fma_f32 v[236:237], v[254:255], v[236:237], s[52:53] op_sel_hi:[1,1,0]
	v_exp_f32_e32 v245, v245
	v_exp_f32_e32 v239, v239
	v_pk_fma_f32 v[242:243], v[246:247], v[242:243], s[54:55] op_sel_hi:[1,1,0]
	v_pk_fma_f32 v[236:237], v[254:255], v[236:237], s[54:55] op_sel_hi:[1,1,0]
	v_pk_fma_f32 v[242:243], v[246:247], v[242:243], s[56:57] op_sel_hi:[1,1,0]
	v_pk_fma_f32 v[236:237], v[254:255], v[236:237], s[56:57] op_sel_hi:[1,1,0]
	v_pk_mul_f32 v[242:243], v[246:247], v[242:243]
	v_pk_mul_f32 v[236:237], v[254:255], v[236:237]
	v_pk_mul_f32 v[242:243], v[242:243], v[244:245]
	v_pk_mul_f32 v[236:237], v[236:237], v[238:239]
	v_max_f32_e32 v246, 0, v66
	v_max_f32_e32 v254, 0, v68
	v_max_f32_e32 v247, 0, v67
	v_max_f32_e32 v255, 0, v69
	v_fma_f32 v84, -|v66|, v242, v246
	v_fma_f32 v86, -|v68|, v236, v254
	v_fma_f32 v85, -|v67|, v243, v247
	v_fma_f32 v87, -|v69|, v237, v255
	s_and_b64 vcc, exec, s[8:9]
	s_cbranch_vccz .LBB0_368
	s_branch .LBB0_369

.LBB0_395:
	v_mov_b64_e32 v[232:233], s[50:51]
	v_fma_f32 v234, |v62|, s36, 1.0
	v_fma_f32 v240, |v68|, s36, 1.0
	v_fma_f32 v235, |v63|, s36, 1.0
	v_fma_f32 v241, |v69|, s36, 1.0
	v_pk_mul_f32 v[238:239], v[62:63], v[62:63]
	v_pk_mul_f32 v[244:245], v[68:69], v[68:69]
	v_rcp_f32_e32 v234, v234
	v_rcp_f32_e32 v240, v240
	v_rcp_f32_e32 v235, v235
	v_rcp_f32_e32 v241, v241
	v_pk_mul_f32 v[238:239], v[238:239], s[58:59] op_sel_hi:[1,0]
	v_pk_mul_f32 v[244:245], v[244:245], s[58:59] op_sel_hi:[1,0]
	v_pk_fma_f32 v[236:237], v[234:235], s[38:39], v[232:233] op_sel_hi:[1,0,0]
	v_pk_fma_f32 v[242:243], v[240:241], s[38:39], v[232:233] op_sel_hi:[1,0,0]
	v_exp_f32_e32 v238, v238
	v_exp_f32_e32 v244, v244
	v_pk_fma_f32 v[236:237], v[234:235], v[236:237], s[52:53] op_sel_hi:[1,1,0]
	v_pk_fma_f32 v[242:243], v[240:241], v[242:243], s[52:53] op_sel_hi:[1,1,0]
	v_exp_f32_e32 v239, v239
	v_exp_f32_e32 v245, v245
	v_pk_fma_f32 v[236:237], v[234:235], v[236:237], s[54:55] op_sel_hi:[1,1,0]
	v_pk_fma_f32 v[242:243], v[240:241], v[242:243], s[54:55] op_sel_hi:[1,1,0]
	v_pk_fma_f32 v[236:237], v[234:235], v[236:237], s[56:57] op_sel_hi:[1,1,0]
	v_pk_fma_f32 v[242:243], v[240:241], v[242:243], s[56:57] op_sel_hi:[1,1,0]
	v_pk_mul_f32 v[236:237], v[234:235], v[236:237]
	v_pk_mul_f32 v[242:243], v[240:241], v[242:243]
	v_pk_mul_f32 v[236:237], v[236:237], v[238:239]
	v_pk_mul_f32 v[242:243], v[242:243], v[244:245]
	v_max_f32_e32 v234, 0, v62
	v_max_f32_e32 v240, 0, v68
	v_max_f32_e32 v235, 0, v63
	v_max_f32_e32 v241, 0, v69
	v_fma_f32 v64, -|v62|, v236, v234
	v_fma_f32 v66, -|v68|, v242, v240
	v_fma_f32 v65, -|v63|, v237, v235
	v_fma_f32 v67, -|v69|, v243, v241
	v_fma_f32 v246, |v58|, s36, 1.0
	v_fma_f32 v254, |v60|, s36, 1.0
	v_fma_f32 v247, |v59|, s36, 1.0
	v_fma_f32 v255, |v61|, s36, 1.0
	v_pk_mul_f32 v[244:245], v[58:59], v[58:59]
	v_pk_mul_f32 v[238:239], v[60:61], v[60:61]
	v_rcp_f32_e32 v246, v246
	v_rcp_f32_e32 v254, v254
	v_rcp_f32_e32 v247, v247
	v_rcp_f32_e32 v255, v255
	v_pk_mul_f32 v[244:245], v[244:245], s[58:59] op_sel_hi:[1,0]
	v_pk_mul_f32 v[238:239], v[238:239], s[58:59] op_sel_hi:[1,0]
	v_pk_fma_f32 v[242:243], v[246:247], s[38:39], v[232:233] op_sel_hi:[1,0,0]
	v_pk_fma_f32 v[236:237], v[254:255], s[38:39], v[232:233] op_sel_hi:[1,0,0]
	v_exp_f32_e32 v244, v244
	v_exp_f32_e32 v238, v238
	v_pk_fma_f32 v[242:243], v[246:247], v[242:243], s[52:53] op_sel_hi:[1,1,0]
	v_pk_fma_f32 v[236:237], v[254:255], v[236:237], s[52:53] op_sel_hi:[1,1,0]
	v_exp_f32_e32 v245, v245
	v_exp_f32_e32 v239, v239
	v_pk_fma_f32 v[242:243], v[246:247], v[242:243], s[54:55] op_sel_hi:[1,1,0]
	v_pk_fma_f32 v[236:237], v[254:255], v[236:237], s[54:55] op_sel_hi:[1,1,0]
	v_pk_fma_f32 v[242:243], v[246:247], v[242:243], s[56:57] op_sel_hi:[1,1,0]
	v_pk_fma_f32 v[236:237], v[254:255], v[236:237], s[56:57] op_sel_hi:[1,1,0]
	v_pk_mul_f32 v[242:243], v[246:247], v[242:243]
	v_pk_mul_f32 v[236:237], v[254:255], v[236:237]
	v_pk_mul_f32 v[242:243], v[242:243], v[244:245]
	v_pk_mul_f32 v[236:237], v[236:237], v[238:239]
	v_max_f32_e32 v246, 0, v58
	v_max_f32_e32 v254, 0, v60
	v_max_f32_e32 v247, 0, v59
	v_max_f32_e32 v255, 0, v61
	v_fma_f32 v70, -|v58|, v242, v246
	v_fma_f32 v72, -|v60|, v236, v254
	v_fma_f32 v71, -|v59|, v243, v247
	v_fma_f32 v73, -|v61|, v237, v255
	s_and_b64 vcc, exec, s[10:11]
	s_cbranch_vccz .LBB0_376

.LBB0_419:
	v_mov_b64_e32 v[232:233], s[50:51]
	v_fma_f32 v234, |v66|, s36, 1.0
	v_fma_f32 v240, |v56|, s36, 1.0
	v_fma_f32 v235, |v67|, s36, 1.0
	v_fma_f32 v241, |v57|, s36, 1.0
	v_pk_mul_f32 v[238:239], v[66:67], v[66:67]
	v_pk_mul_f32 v[244:245], v[56:57], v[56:57]
	v_rcp_f32_e32 v234, v234
	v_rcp_f32_e32 v240, v240
	v_rcp_f32_e32 v235, v235
	v_rcp_f32_e32 v241, v241
	v_pk_mul_f32 v[238:239], v[238:239], s[58:59] op_sel_hi:[1,0]
	v_pk_mul_f32 v[244:245], v[244:245], s[58:59] op_sel_hi:[1,0]
	v_pk_fma_f32 v[236:237], v[234:235], s[38:39], v[232:233] op_sel_hi:[1,0,0]
	v_pk_fma_f32 v[242:243], v[240:241], s[38:39], v[232:233] op_sel_hi:[1,0,0]
	v_exp_f32_e32 v238, v238
	v_exp_f32_e32 v244, v244
	v_pk_fma_f32 v[236:237], v[234:235], v[236:237], s[52:53] op_sel_hi:[1,1,0]
	v_pk_fma_f32 v[242:243], v[240:241], v[242:243], s[52:53] op_sel_hi:[1,1,0]
	v_exp_f32_e32 v239, v239
	v_exp_f32_e32 v245, v245
	v_pk_fma_f32 v[236:237], v[234:235], v[236:237], s[54:55] op_sel_hi:[1,1,0]
	v_pk_fma_f32 v[242:243], v[240:241], v[242:243], s[54:55] op_sel_hi:[1,1,0]
	v_pk_fma_f32 v[236:237], v[234:235], v[236:237], s[56:57] op_sel_hi:[1,1,0]
	v_pk_fma_f32 v[242:243], v[240:241], v[242:243], s[56:57] op_sel_hi:[1,1,0]
	v_pk_mul_f32 v[236:237], v[234:235], v[236:237]
	v_pk_mul_f32 v[242:243], v[240:241], v[242:243]
	v_pk_mul_f32 v[236:237], v[236:237], v[238:239]
	v_pk_mul_f32 v[242:243], v[242:243], v[244:245]
	v_max_f32_e32 v234, 0, v66
	v_max_f32_e32 v240, 0, v56
	v_max_f32_e32 v235, 0, v67
	v_max_f32_e32 v241, 0, v57
	v_fma_f32 v54, -|v66|, v236, v234
	v_fma_f32 v64, -|v56|, v242, v240
	v_fma_f32 v55, -|v67|, v237, v235
	v_fma_f32 v65, -|v57|, v243, v241
	v_fma_f32 v246, |v50|, s36, 1.0
	v_fma_f32 v254, |v52|, s36, 1.0
	v_fma_f32 v247, |v51|, s36, 1.0
	v_fma_f32 v255, |v53|, s36, 1.0
	v_pk_mul_f32 v[244:245], v[50:51], v[50:51]
	v_pk_mul_f32 v[238:239], v[52:53], v[52:53]
	v_rcp_f32_e32 v246, v246
	v_rcp_f32_e32 v254, v254
	v_rcp_f32_e32 v247, v247
	v_rcp_f32_e32 v255, v255
	v_pk_mul_f32 v[244:245], v[244:245], s[58:59] op_sel_hi:[1,0]
	v_pk_mul_f32 v[238:239], v[238:239], s[58:59] op_sel_hi:[1,0]
	v_pk_fma_f32 v[242:243], v[246:247], s[38:39], v[232:233] op_sel_hi:[1,0,0]
	v_pk_fma_f32 v[236:237], v[254:255], s[38:39], v[232:233] op_sel_hi:[1,0,0]
	v_exp_f32_e32 v244, v244
	v_exp_f32_e32 v238, v238
	v_pk_fma_f32 v[242:243], v[246:247], v[242:243], s[52:53] op_sel_hi:[1,1,0]
	v_pk_fma_f32 v[236:237], v[254:255], v[236:237], s[52:53] op_sel_hi:[1,1,0]
	v_exp_f32_e32 v245, v245
	v_exp_f32_e32 v239, v239
	v_pk_fma_f32 v[242:243], v[246:247], v[242:243], s[54:55] op_sel_hi:[1,1,0]
	v_pk_fma_f32 v[236:237], v[254:255], v[236:237], s[54:55] op_sel_hi:[1,1,0]
	v_pk_fma_f32 v[242:243], v[246:247], v[242:243], s[56:57] op_sel_hi:[1,1,0]
	v_pk_fma_f32 v[236:237], v[254:255], v[236:237], s[56:57] op_sel_hi:[1,1,0]
	v_pk_mul_f32 v[242:243], v[246:247], v[242:243]
	v_pk_mul_f32 v[236:237], v[254:255], v[236:237]
	v_pk_mul_f32 v[242:243], v[242:243], v[244:245]
	v_pk_mul_f32 v[236:237], v[236:237], v[238:239]
	v_max_f32_e32 v246, 0, v50
	v_max_f32_e32 v254, 0, v52
	v_max_f32_e32 v247, 0, v51
	v_max_f32_e32 v255, 0, v53
	v_fma_f32 v68, -|v50|, v242, v246
	v_fma_f32 v70, -|v52|, v236, v254
	v_fma_f32 v69, -|v51|, v243, v247
	v_fma_f32 v71, -|v53|, v237, v255
	s_and_b64 vcc, exec, s[8:9]
	s_cbranch_vccz .LBB0_401
	s_branch .LBB0_402

.LBB0_428:
	v_mov_b64_e32 v[232:233], s[50:51]
	v_fma_f32 v234, |v46|, s36, 1.0
	v_fma_f32 v240, |v52|, s36, 1.0
	v_fma_f32 v235, |v47|, s36, 1.0
	v_fma_f32 v241, |v53|, s36, 1.0
	v_pk_mul_f32 v[238:239], v[46:47], v[46:47]
	v_pk_mul_f32 v[244:245], v[52:53], v[52:53]
	v_rcp_f32_e32 v234, v234
	v_rcp_f32_e32 v240, v240
	v_rcp_f32_e32 v235, v235
	v_rcp_f32_e32 v241, v241
	v_pk_mul_f32 v[238:239], v[238:239], s[58:59] op_sel_hi:[1,0]
	v_pk_mul_f32 v[244:245], v[244:245], s[58:59] op_sel_hi:[1,0]
	v_pk_fma_f32 v[236:237], v[234:235], s[38:39], v[232:233] op_sel_hi:[1,0,0]
	v_pk_fma_f32 v[242:243], v[240:241], s[38:39], v[232:233] op_sel_hi:[1,0,0]
	v_exp_f32_e32 v238, v238
	v_exp_f32_e32 v244, v244
	v_pk_fma_f32 v[236:237], v[234:235], v[236:237], s[52:53] op_sel_hi:[1,1,0]
	v_pk_fma_f32 v[242:243], v[240:241], v[242:243], s[52:53] op_sel_hi:[1,1,0]
	v_exp_f32_e32 v239, v239
	v_exp_f32_e32 v245, v245
	v_pk_fma_f32 v[236:237], v[234:235], v[236:237], s[54:55] op_sel_hi:[1,1,0]
	v_pk_fma_f32 v[242:243], v[240:241], v[242:243], s[54:55] op_sel_hi:[1,1,0]
	v_pk_fma_f32 v[236:237], v[234:235], v[236:237], s[56:57] op_sel_hi:[1,1,0]
	v_pk_fma_f32 v[242:243], v[240:241], v[242:243], s[56:57] op_sel_hi:[1,1,0]
	v_pk_mul_f32 v[236:237], v[234:235], v[236:237]
	v_pk_mul_f32 v[242:243], v[240:241], v[242:243]
	v_pk_mul_f32 v[236:237], v[236:237], v[238:239]
	v_pk_mul_f32 v[242:243], v[242:243], v[244:245]
	v_max_f32_e32 v234, 0, v46
	v_max_f32_e32 v240, 0, v52
	v_max_f32_e32 v235, 0, v47
	v_max_f32_e32 v241, 0, v53
	v_fma_f32 v48, -|v46|, v236, v234
	v_fma_f32 v50, -|v52|, v242, v240
	v_fma_f32 v49, -|v47|, v237, v235
	v_fma_f32 v51, -|v53|, v243, v241
	v_fma_f32 v246, |v42|, s36, 1.0
	v_fma_f32 v254, |v44|, s36, 1.0
	v_fma_f32 v247, |v43|, s36, 1.0
	v_fma_f32 v255, |v45|, s36, 1.0
	v_pk_mul_f32 v[244:245], v[42:43], v[42:43]
	v_pk_mul_f32 v[238:239], v[44:45], v[44:45]
	v_rcp_f32_e32 v246, v246
	v_rcp_f32_e32 v254, v254
	v_rcp_f32_e32 v247, v247
	v_rcp_f32_e32 v255, v255
	v_pk_mul_f32 v[244:245], v[244:245], s[58:59] op_sel_hi:[1,0]
	v_pk_mul_f32 v[238:239], v[238:239], s[58:59] op_sel_hi:[1,0]
	v_pk_fma_f32 v[242:243], v[246:247], s[38:39], v[232:233] op_sel_hi:[1,0,0]
	v_pk_fma_f32 v[236:237], v[254:255], s[38:39], v[232:233] op_sel_hi:[1,0,0]
	v_exp_f32_e32 v244, v244
	v_exp_f32_e32 v238, v238
	v_pk_fma_f32 v[242:243], v[246:247], v[242:243], s[52:53] op_sel_hi:[1,1,0]
	v_pk_fma_f32 v[236:237], v[254:255], v[236:237], s[52:53] op_sel_hi:[1,1,0]
	v_exp_f32_e32 v245, v245
	v_exp_f32_e32 v239, v239
	v_pk_fma_f32 v[242:243], v[246:247], v[242:243], s[54:55] op_sel_hi:[1,1,0]
	v_pk_fma_f32 v[236:237], v[254:255], v[236:237], s[54:55] op_sel_hi:[1,1,0]
	v_pk_fma_f32 v[242:243], v[246:247], v[242:243], s[56:57] op_sel_hi:[1,1,0]
	v_pk_fma_f32 v[236:237], v[254:255], v[236:237], s[56:57] op_sel_hi:[1,1,0]
	v_pk_mul_f32 v[242:243], v[246:247], v[242:243]
	v_pk_mul_f32 v[236:237], v[254:255], v[236:237]
	v_pk_mul_f32 v[242:243], v[242:243], v[244:245]
	v_pk_mul_f32 v[236:237], v[236:237], v[238:239]
	v_max_f32_e32 v246, 0, v42
	v_max_f32_e32 v254, 0, v44
	v_max_f32_e32 v247, 0, v43
	v_max_f32_e32 v255, 0, v45
	v_fma_f32 v54, -|v42|, v242, v246
	v_fma_f32 v56, -|v44|, v236, v254
	v_fma_f32 v55, -|v43|, v243, v247
	v_fma_f32 v57, -|v45|, v237, v255
	s_and_b64 vcc, exec, s[10:11]
	s_cbranch_vccz .LBB0_409

.LBB0_452:
	v_mov_b64_e32 v[232:233], s[50:51]
	v_fma_f32 v234, |v50|, s36, 1.0
	v_fma_f32 v240, |v32|, s36, 1.0
	v_fma_f32 v235, |v51|, s36, 1.0
	v_fma_f32 v241, |v33|, s36, 1.0
	v_pk_mul_f32 v[238:239], v[50:51], v[50:51]
	v_pk_mul_f32 v[244:245], v[32:33], v[32:33]
	v_rcp_f32_e32 v234, v234
	v_rcp_f32_e32 v240, v240
	v_rcp_f32_e32 v235, v235
	v_rcp_f32_e32 v241, v241
	v_pk_mul_f32 v[238:239], v[238:239], s[58:59] op_sel_hi:[1,0]
	v_pk_mul_f32 v[244:245], v[244:245], s[58:59] op_sel_hi:[1,0]
	v_pk_fma_f32 v[236:237], v[234:235], s[38:39], v[232:233] op_sel_hi:[1,0,0]
	v_pk_fma_f32 v[242:243], v[240:241], s[38:39], v[232:233] op_sel_hi:[1,0,0]
	v_exp_f32_e32 v238, v238
	v_exp_f32_e32 v244, v244
	v_pk_fma_f32 v[236:237], v[234:235], v[236:237], s[52:53] op_sel_hi:[1,1,0]
	v_pk_fma_f32 v[242:243], v[240:241], v[242:243], s[52:53] op_sel_hi:[1,1,0]
	v_exp_f32_e32 v239, v239
	v_exp_f32_e32 v245, v245
	v_pk_fma_f32 v[236:237], v[234:235], v[236:237], s[54:55] op_sel_hi:[1,1,0]
	v_pk_fma_f32 v[242:243], v[240:241], v[242:243], s[54:55] op_sel_hi:[1,1,0]
	v_pk_fma_f32 v[236:237], v[234:235], v[236:237], s[56:57] op_sel_hi:[1,1,0]
	v_pk_fma_f32 v[242:243], v[240:241], v[242:243], s[56:57] op_sel_hi:[1,1,0]
	v_pk_mul_f32 v[236:237], v[234:235], v[236:237]
	v_pk_mul_f32 v[242:243], v[240:241], v[242:243]
	v_pk_mul_f32 v[236:237], v[236:237], v[238:239]
	v_pk_mul_f32 v[242:243], v[242:243], v[244:245]
	v_max_f32_e32 v234, 0, v50
	v_max_f32_e32 v240, 0, v32
	v_max_f32_e32 v235, 0, v51
	v_max_f32_e32 v241, 0, v33
	v_fma_f32 v30, -|v50|, v236, v234
	v_fma_f32 v48, -|v32|, v242, v240
	v_fma_f32 v31, -|v51|, v237, v235
	v_fma_f32 v49, -|v33|, v243, v241
	v_fma_f32 v246, |v26|, s36, 1.0
	v_fma_f32 v254, |v28|, s36, 1.0
	v_fma_f32 v247, |v27|, s36, 1.0
	v_fma_f32 v255, |v29|, s36, 1.0
	v_pk_mul_f32 v[244:245], v[26:27], v[26:27]
	v_pk_mul_f32 v[238:239], v[28:29], v[28:29]
	v_rcp_f32_e32 v246, v246
	v_rcp_f32_e32 v254, v254
	v_rcp_f32_e32 v247, v247
	v_rcp_f32_e32 v255, v255
	v_pk_mul_f32 v[244:245], v[244:245], s[58:59] op_sel_hi:[1,0]
	v_pk_mul_f32 v[238:239], v[238:239], s[58:59] op_sel_hi:[1,0]
	v_pk_fma_f32 v[242:243], v[246:247], s[38:39], v[232:233] op_sel_hi:[1,0,0]
	v_pk_fma_f32 v[236:237], v[254:255], s[38:39], v[232:233] op_sel_hi:[1,0,0]
	v_exp_f32_e32 v244, v244
	v_exp_f32_e32 v238, v238
	v_pk_fma_f32 v[242:243], v[246:247], v[242:243], s[52:53] op_sel_hi:[1,1,0]
	v_pk_fma_f32 v[236:237], v[254:255], v[236:237], s[52:53] op_sel_hi:[1,1,0]
	v_exp_f32_e32 v245, v245
	v_exp_f32_e32 v239, v239
	v_pk_fma_f32 v[242:243], v[246:247], v[242:243], s[54:55] op_sel_hi:[1,1,0]
	v_pk_fma_f32 v[236:237], v[254:255], v[236:237], s[54:55] op_sel_hi:[1,1,0]
	v_pk_fma_f32 v[242:243], v[246:247], v[242:243], s[56:57] op_sel_hi:[1,1,0]
	v_pk_fma_f32 v[236:237], v[254:255], v[236:237], s[56:57] op_sel_hi:[1,1,0]
	v_pk_mul_f32 v[242:243], v[246:247], v[242:243]
	v_pk_mul_f32 v[236:237], v[254:255], v[236:237]
	v_pk_mul_f32 v[242:243], v[242:243], v[244:245]
	v_pk_mul_f32 v[236:237], v[236:237], v[238:239]
	v_max_f32_e32 v246, 0, v26
	v_max_f32_e32 v254, 0, v28
	v_max_f32_e32 v247, 0, v27
	v_max_f32_e32 v255, 0, v29
	v_fma_f32 v52, -|v26|, v242, v246
	v_fma_f32 v54, -|v28|, v236, v254
	v_fma_f32 v53, -|v27|, v243, v247
	v_fma_f32 v55, -|v29|, v237, v255
	s_and_b64 vcc, exec, s[8:9]
	s_cbranch_vccz .LBB0_434
	s_branch .LBB0_435

.LBB0_461:
	s_waitcnt lgkmcnt(0)
	v_mov_b64_e32 v[232:233], s[50:51]
	v_fma_f32 v234, |v30|, s36, 1.0
	v_fma_f32 v240, |v16|, s36, 1.0
	v_fma_f32 v235, |v31|, s36, 1.0
	v_fma_f32 v241, |v17|, s36, 1.0
	v_pk_mul_f32 v[238:239], v[30:31], v[30:31]
	v_pk_mul_f32 v[244:245], v[16:17], v[16:17]
	v_rcp_f32_e32 v234, v234
	v_rcp_f32_e32 v240, v240
	v_rcp_f32_e32 v235, v235
	v_rcp_f32_e32 v241, v241
	v_pk_mul_f32 v[238:239], v[238:239], s[58:59] op_sel_hi:[1,0]
	v_pk_mul_f32 v[244:245], v[244:245], s[58:59] op_sel_hi:[1,0]
	v_pk_fma_f32 v[236:237], v[234:235], s[38:39], v[232:233] op_sel_hi:[1,0,0]
	v_pk_fma_f32 v[242:243], v[240:241], s[38:39], v[232:233] op_sel_hi:[1,0,0]
	v_exp_f32_e32 v238, v238
	v_exp_f32_e32 v244, v244
	v_pk_fma_f32 v[236:237], v[234:235], v[236:237], s[52:53] op_sel_hi:[1,1,0]
	v_pk_fma_f32 v[242:243], v[240:241], v[242:243], s[52:53] op_sel_hi:[1,1,0]
	v_exp_f32_e32 v239, v239
	v_exp_f32_e32 v245, v245
	v_pk_fma_f32 v[236:237], v[234:235], v[236:237], s[54:55] op_sel_hi:[1,1,0]
	v_pk_fma_f32 v[242:243], v[240:241], v[242:243], s[54:55] op_sel_hi:[1,1,0]
	v_pk_fma_f32 v[236:237], v[234:235], v[236:237], s[56:57] op_sel_hi:[1,1,0]
	v_pk_fma_f32 v[242:243], v[240:241], v[242:243], s[56:57] op_sel_hi:[1,1,0]
	v_pk_mul_f32 v[236:237], v[234:235], v[236:237]
	v_pk_mul_f32 v[242:243], v[240:241], v[242:243]
	v_pk_mul_f32 v[236:237], v[236:237], v[238:239]
	v_pk_mul_f32 v[242:243], v[242:243], v[244:245]
	v_max_f32_e32 v234, 0, v30
	v_max_f32_e32 v240, 0, v16
	v_max_f32_e32 v235, 0, v31
	v_max_f32_e32 v241, 0, v17
	v_fma_f32 v14, -|v30|, v236, v234
	v_fma_f32 v26, -|v16|, v242, v240
	v_fma_f32 v15, -|v31|, v237, v235
	v_fma_f32 v27, -|v17|, v243, v241
	v_fma_f32 v246, |v12|, s36, 1.0
	v_fma_f32 v254, |v10|, s36, 1.0
	v_fma_f32 v247, |v13|, s36, 1.0
	v_fma_f32 v255, |v11|, s36, 1.0
	v_pk_mul_f32 v[244:245], v[12:13], v[12:13]
	v_pk_mul_f32 v[238:239], v[10:11], v[10:11]
	v_rcp_f32_e32 v246, v246
	v_rcp_f32_e32 v254, v254
	v_rcp_f32_e32 v247, v247
	v_rcp_f32_e32 v255, v255
	v_pk_mul_f32 v[244:245], v[244:245], s[58:59] op_sel_hi:[1,0]
	v_pk_mul_f32 v[238:239], v[238:239], s[58:59] op_sel_hi:[1,0]
	v_pk_fma_f32 v[242:243], v[246:247], s[38:39], v[232:233] op_sel_hi:[1,0,0]
	v_pk_fma_f32 v[236:237], v[254:255], s[38:39], v[232:233] op_sel_hi:[1,0,0]
	v_exp_f32_e32 v244, v244
	v_exp_f32_e32 v238, v238
	v_pk_fma_f32 v[242:243], v[246:247], v[242:243], s[52:53] op_sel_hi:[1,1,0]
	v_pk_fma_f32 v[236:237], v[254:255], v[236:237], s[52:53] op_sel_hi:[1,1,0]
	v_exp_f32_e32 v245, v245
	v_exp_f32_e32 v239, v239
	v_pk_fma_f32 v[242:243], v[246:247], v[242:243], s[54:55] op_sel_hi:[1,1,0]
	v_pk_fma_f32 v[236:237], v[254:255], v[236:237], s[54:55] op_sel_hi:[1,1,0]
	v_pk_fma_f32 v[242:243], v[246:247], v[242:243], s[56:57] op_sel_hi:[1,1,0]
	v_pk_fma_f32 v[236:237], v[254:255], v[236:237], s[56:57] op_sel_hi:[1,1,0]
	v_pk_mul_f32 v[242:243], v[246:247], v[242:243]
	v_pk_mul_f32 v[236:237], v[254:255], v[236:237]
	v_pk_mul_f32 v[242:243], v[242:243], v[244:245]
	v_pk_mul_f32 v[236:237], v[236:237], v[238:239]
	v_max_f32_e32 v246, 0, v12
	v_max_f32_e32 v254, 0, v10
	v_max_f32_e32 v247, 0, v13
	v_max_f32_e32 v255, 0, v11
	v_fma_f32 v32, -|v12|, v242, v246
	v_fma_f32 v28, -|v10|, v236, v254
	v_fma_f32 v33, -|v13|, v243, v247
	v_fma_f32 v29, -|v11|, v237, v255
	s_and_b64 vcc, exec, s[10:11]
	s_cbranch_vccz .LBB0_442

.LBB0_483:
	v_mov_b64_e32 v[232:233], s[50:51]
	v_fma_f32 v234, |v14|, s36, 1.0
	v_fma_f32 v240, |v8|, s36, 1.0
	v_fma_f32 v235, |v15|, s36, 1.0
	v_fma_f32 v241, |v9|, s36, 1.0
	v_pk_mul_f32 v[238:239], v[14:15], v[14:15]
	v_pk_mul_f32 v[244:245], v[8:9], v[8:9]
	v_rcp_f32_e32 v234, v234
	v_rcp_f32_e32 v240, v240
	v_rcp_f32_e32 v235, v235
	v_rcp_f32_e32 v241, v241
	v_pk_mul_f32 v[238:239], v[238:239], s[58:59] op_sel_hi:[1,0]
	v_pk_mul_f32 v[244:245], v[244:245], s[58:59] op_sel_hi:[1,0]
	v_pk_fma_f32 v[236:237], v[234:235], s[38:39], v[232:233] op_sel_hi:[1,0,0]
	v_pk_fma_f32 v[242:243], v[240:241], s[38:39], v[232:233] op_sel_hi:[1,0,0]
	v_exp_f32_e32 v238, v238
	v_exp_f32_e32 v244, v244
	v_pk_fma_f32 v[236:237], v[234:235], v[236:237], s[52:53] op_sel_hi:[1,1,0]
	v_pk_fma_f32 v[242:243], v[240:241], v[242:243], s[52:53] op_sel_hi:[1,1,0]
	v_exp_f32_e32 v239, v239
	v_exp_f32_e32 v245, v245
	v_pk_fma_f32 v[236:237], v[234:235], v[236:237], s[54:55] op_sel_hi:[1,1,0]
	v_pk_fma_f32 v[242:243], v[240:241], v[242:243], s[54:55] op_sel_hi:[1,1,0]
	v_pk_fma_f32 v[236:237], v[234:235], v[236:237], s[56:57] op_sel_hi:[1,1,0]
	v_pk_fma_f32 v[242:243], v[240:241], v[242:243], s[56:57] op_sel_hi:[1,1,0]
	v_pk_mul_f32 v[236:237], v[234:235], v[236:237]
	v_pk_mul_f32 v[242:243], v[240:241], v[242:243]
	v_pk_mul_f32 v[236:237], v[236:237], v[238:239]
	v_pk_mul_f32 v[242:243], v[242:243], v[244:245]
	v_max_f32_e32 v234, 0, v14
	v_max_f32_e32 v240, 0, v8
	v_max_f32_e32 v235, 0, v15
	v_max_f32_e32 v241, 0, v9
	v_fma_f32 v6, -|v14|, v236, v234
	v_fma_f32 v18, -|v8|, v242, v240
	v_fma_f32 v7, -|v15|, v237, v235
	v_fma_f32 v19, -|v9|, v243, v241
	v_fma_f32 v246, |v4|, s36, 1.0
	v_fma_f32 v254, |v2|, s36, 1.0
	v_fma_f32 v247, |v5|, s36, 1.0
	v_fma_f32 v255, |v3|, s36, 1.0
	v_pk_mul_f32 v[244:245], v[4:5], v[4:5]
	v_pk_mul_f32 v[238:239], v[2:3], v[2:3]
	v_rcp_f32_e32 v246, v246
	v_rcp_f32_e32 v254, v254
	v_rcp_f32_e32 v247, v247
	v_rcp_f32_e32 v255, v255
	v_pk_mul_f32 v[244:245], v[244:245], s[58:59] op_sel_hi:[1,0]
	v_pk_mul_f32 v[238:239], v[238:239], s[58:59] op_sel_hi:[1,0]
	v_pk_fma_f32 v[242:243], v[246:247], s[38:39], v[232:233] op_sel_hi:[1,0,0]
	v_pk_fma_f32 v[236:237], v[254:255], s[38:39], v[232:233] op_sel_hi:[1,0,0]
	v_exp_f32_e32 v244, v244
	v_exp_f32_e32 v238, v238
	v_pk_fma_f32 v[242:243], v[246:247], v[242:243], s[52:53] op_sel_hi:[1,1,0]
	v_pk_fma_f32 v[236:237], v[254:255], v[236:237], s[52:53] op_sel_hi:[1,1,0]
	v_exp_f32_e32 v245, v245
	v_exp_f32_e32 v239, v239
	v_pk_fma_f32 v[242:243], v[246:247], v[242:243], s[54:55] op_sel_hi:[1,1,0]
	v_pk_fma_f32 v[236:237], v[254:255], v[236:237], s[54:55] op_sel_hi:[1,1,0]
	v_pk_fma_f32 v[242:243], v[246:247], v[242:243], s[56:57] op_sel_hi:[1,1,0]
	v_pk_fma_f32 v[236:237], v[254:255], v[236:237], s[56:57] op_sel_hi:[1,1,0]
	v_pk_mul_f32 v[242:243], v[246:247], v[242:243]
	v_pk_mul_f32 v[236:237], v[254:255], v[236:237]
	v_pk_mul_f32 v[242:243], v[242:243], v[244:245]
	v_pk_mul_f32 v[236:237], v[236:237], v[238:239]
	v_max_f32_e32 v246, 0, v4
	v_max_f32_e32 v254, 0, v2
	v_max_f32_e32 v247, 0, v5
	v_max_f32_e32 v255, 0, v3
	v_fma_f32 v22, -|v4|, v242, v246
	v_fma_f32 v20, -|v2|, v236, v254
	v_fma_f32 v23, -|v5|, v243, v247
	v_fma_f32 v21, -|v3|, v237, v255
	s_and_b64 vcc, exec, s[8:9]
	s_cbranch_vccz .LBB0_467
	s_branch .LBB0_468
